# tile-list OR reduction via DPP/permlane only (A/B)
# speedup vs baseline: 1.0089x; 1.0009x over previous
; DI void attn_unit(LAS unsigned char* lds, const Args& a, int bg, int qt) {
;     ...
;         for (int it = 0; it < 4; ++it) { const int q = (tid >> 5) + 16 * it;
;             float v = 0.f;
; #pragma unroll
;             for (int h = 0; h < 4; ++h) { const int hq = h * 64 + q; const float sc = SCL[hq * 3 + (j >> 4)]; v += IMP[hq * IMP_PITCH + j] * sc + ((j == 16) ? SCL[hq * 3 + 2] : 0.f); }
;             const bool forced = (j == 0) || (j == qt) || (j == qt - 1);
;             v = forced ? 1e4f : (j > qt ? -1.0f : v);
;             VAL[q * 32 + j] = v; }
.LBB0_817:
	ds_read_b32 v35, v193
	ds_read_b32 v38, v240
	v_mov_b32_e32 v34, 0
	v_mov_b32_e32 v39, 0
	s_and_saveexec_b64 s[10:11], s[4:5]
	ds_read_b32 v39, v192 offset:8
	s_or_b64 exec, exec, s[10:11]
	ds_read_b32 v40, v195
	ds_read_b32 v41, v240 offset:8448
	s_and_saveexec_b64 s[10:11], s[4:5]
	ds_read_b32 v34, v194 offset:8
	s_or_b64 exec, exec, s[10:11]
	ds_read_b32 v43, v197
	ds_read_b32 v44, v240 offset:16896
	v_mov_b32_e32 v42, 0
	v_mov_b32_e32 v45, 0
	s_and_saveexec_b64 s[10:11], s[4:5]
	ds_read_b32 v45, v196 offset:8
	s_or_b64 exec, exec, s[10:11]
	ds_read_b32 v46, v199
	ds_read_b32 v47, v240 offset:25344
	s_and_saveexec_b64 s[10:11], s[4:5]
	ds_read_b32 v42, v198 offset:8
	s_or_b64 exec, exec, s[10:11]
	s_waitcnt lgkmcnt(6)
	v_fmac_f32_e32 v39, v35, v38
	v_add_f32_e32 v35, 0, v39
	s_waitcnt lgkmcnt(4)
	v_fmac_f32_e32 v34, v40, v41
	v_add_f32_e32 v34, v35, v34
	s_waitcnt lgkmcnt(2)
	v_fmac_f32_e32 v45, v43, v44
	v_add_f32_e32 v34, v34, v45
	v_cmp_eq_u32_e32 vcc, s73, v98
	s_add_i32 s10, s73, -1
	s_waitcnt lgkmcnt(0)
	v_fmac_f32_e32 v42, v46, v47
	s_or_b64 s[12:13], s[6:7], vcc
	v_cmp_eq_u32_e64 s[10:11], s10, v98
	v_add_f32_e32 v34, v34, v42
	v_cmp_lt_u32_e32 vcc, s73, v98
	s_or_b64 s[10:11], s[12:13], s[10:11]
	v_mov_b32_e32 v39, 0
	v_cndmask_b32_e64 v34, v34, -1.0, vcc
	v_cndmask_b32_e64 v34, v34, v241, s[10:11]
	ds_write_b32 v224, v34
	ds_read_b32 v35, v201
	ds_read_b32 v38, v240 offset:2112
	v_mov_b32_e32 v34, 0
	s_and_saveexec_b64 s[12:13], s[4:5]
	ds_read_b32 v39, v200 offset:8
	s_or_b64 exec, exec, s[12:13]
	ds_read_b32 v40, v203
	ds_read_b32 v41, v240 offset:10560
	s_and_saveexec_b64 s[12:13], s[4:5]
	ds_read_b32 v34, v202 offset:8
	s_or_b64 exec, exec, s[12:13]
	ds_read_b32 v43, v205
	ds_read_b32 v44, v240 offset:19008
	v_mov_b32_e32 v42, 0
	v_mov_b32_e32 v45, 0
	s_and_saveexec_b64 s[12:13], s[4:5]
	ds_read_b32 v45, v204 offset:8
	s_or_b64 exec, exec, s[12:13]
	ds_read_b32 v46, v207
	ds_read_b32 v47, v240 offset:27456
	s_and_saveexec_b64 s[12:13], s[4:5]
	ds_read_b32 v42, v206 offset:8
	s_or_b64 exec, exec, s[12:13]
	s_waitcnt lgkmcnt(6)
	v_fmac_f32_e32 v39, v35, v38
	v_add_f32_e32 v35, 0, v39
	s_waitcnt lgkmcnt(4)
	v_fmac_f32_e32 v34, v40, v41
	v_add_f32_e32 v34, v35, v34
	s_waitcnt lgkmcnt(2)
	v_fmac_f32_e32 v45, v43, v44
	v_add_f32_e32 v34, v34, v45
	s_waitcnt lgkmcnt(0)
	v_fmac_f32_e32 v42, v46, v47
	v_add_f32_e32 v34, v34, v42
	v_cndmask_b32_e64 v34, v34, -1.0, vcc
	v_cndmask_b32_e64 v34, v34, v241, s[10:11]
	ds_write_b32 v226, v34
	ds_read_b32 v35, v209
	ds_read_b32 v38, v240 offset:4224
	v_mov_b32_e32 v34, 0
	v_mov_b32_e32 v39, 0
	s_and_saveexec_b64 s[12:13], s[4:5]
	ds_read_b32 v39, v208 offset:8
	s_or_b64 exec, exec, s[12:13]
	ds_read_b32 v40, v211
	ds_read_b32 v41, v240 offset:12672
	s_and_saveexec_b64 s[12:13], s[4:5]
	ds_read_b32 v34, v210 offset:8
	s_or_b64 exec, exec, s[12:13]
	ds_read_b32 v43, v213
	ds_read_b32 v44, v240 offset:21120
	v_mov_b32_e32 v42, 0
	v_mov_b32_e32 v45, 0
	s_and_saveexec_b64 s[12:13], s[4:5]
	ds_read_b32 v45, v212 offset:8
	s_or_b64 exec, exec, s[12:13]
	ds_read_b32 v46, v215
	ds_read_b32 v47, v240 offset:29568
	s_and_saveexec_b64 s[12:13], s[4:5]
	ds_read_b32 v42, v214 offset:8
	s_or_b64 exec, exec, s[12:13]
	s_waitcnt lgkmcnt(6)
	v_fmac_f32_e32 v39, v35, v38
	v_add_f32_e32 v35, 0, v39
	s_waitcnt lgkmcnt(4)
	v_fmac_f32_e32 v34, v40, v41
	v_add_f32_e32 v34, v35, v34
	s_waitcnt lgkmcnt(2)
	v_fmac_f32_e32 v45, v43, v44
	v_add_f32_e32 v34, v34, v45
	s_waitcnt lgkmcnt(0)
	v_fmac_f32_e32 v42, v46, v47
	v_add_f32_e32 v34, v34, v42
	v_cndmask_b32_e64 v34, v34, -1.0, vcc
	v_cndmask_b32_e64 v34, v34, v241, s[10:11]
	ds_write_b32 v228, v34
	ds_read_b32 v35, v217
	ds_read_b32 v38, v240 offset:6336
	v_mov_b32_e32 v34, 0
	v_mov_b32_e32 v39, 0
	s_and_saveexec_b64 s[12:13], s[4:5]
	ds_read_b32 v39, v216 offset:8
	s_or_b64 exec, exec, s[12:13]
	ds_read_b32 v40, v219
	ds_read_b32 v41, v240 offset:14784
	s_and_saveexec_b64 s[12:13], s[4:5]
	ds_read_b32 v34, v218 offset:8
	s_or_b64 exec, exec, s[12:13]
	ds_read_b32 v43, v221
	ds_read_b32 v44, v240 offset:23232
	v_mov_b32_e32 v42, 0
	v_mov_b32_e32 v45, 0
	s_and_saveexec_b64 s[12:13], s[4:5]
	ds_read_b32 v45, v220 offset:8
	s_or_b64 exec, exec, s[12:13]
	ds_read_b32 v46, v223
	ds_read_b32 v47, v240 offset:31680
	s_and_saveexec_b64 s[12:13], s[4:5]
	ds_read_b32 v42, v222 offset:8
	s_or_b64 exec, exec, s[12:13]
	s_waitcnt lgkmcnt(6)
	v_fmac_f32_e32 v39, v35, v38
	v_add_f32_e32 v35, 0, v39
	s_waitcnt lgkmcnt(4)
	v_fmac_f32_e32 v34, v40, v41
	v_add_f32_e32 v34, v35, v34
	s_waitcnt lgkmcnt(2)
	v_fmac_f32_e32 v45, v43, v44
	v_add_f32_e32 v34, v34, v45
	s_waitcnt lgkmcnt(0)
	v_fmac_f32_e32 v42, v46, v47
	v_add_f32_e32 v34, v34, v42
	v_cndmask_b32_e64 v34, v34, -1.0, vcc
	v_cndmask_b32_e64 v34, v34, v241, s[10:11]
	ds_write_b32 v230, v34
	s_waitcnt lgkmcnt(0)
	s_barrier
; DI void attn_unit(LAS unsigned char* lds, const Args& a, int bg, int qt) {
;     ...
;         for (int it = 0; it < 4; ++it) { const int q = (tid >> 5) + 16 * it;
;             const float v = VAL[q * 32 + j]; int cnt = 0;
; #pragma unroll 8
;             for (int jj = 0; jj < 32; ++jj) { const float ov = VAL[q * 32 + jj]; cnt += ((ov > v) || (ov == v && jj < j)) ? 1 : 0; }
	v_add_u32_e32 v65, 0x18400, v234
	ds_read_b32 v34, v224
	ds_read_b128 v[40:43], v65
	ds_read_b128 v[44:47], v65 offset:16
	ds_read_b128 v[48:51], v65 offset:32
	ds_read_b128 v[52:55], v65 offset:48
	ds_read_b128 v[56:59], v65 offset:64
	ds_read_b128 v[60:63], v65 offset:80
	v_mov_b32_e32 v35, 0
	v_mov_b32_e32 v38, 0
	s_waitcnt lgkmcnt(5)
	v_cmp_gt_f32_e64 s[10:11], v40, v34
	v_cmp_eq_f32_e64 s[12:13], v40, v34
	v_cmp_gt_f32_e64 s[16:17], v41, v34
	v_cmp_eq_f32_e64 s[18:19], v41, v34
	v_addc_co_u32_e64 v35, s[20:21], v35, v35, s[10:11]
	v_addc_co_u32_e64 v38, s[20:21], v38, v38, s[12:13]
	v_addc_co_u32_e64 v35, s[20:21], v35, v35, s[16:17]
	v_addc_co_u32_e64 v38, s[20:21], v38, v38, s[18:19]
	v_cmp_gt_f32_e64 s[10:11], v42, v34
	v_cmp_eq_f32_e64 s[12:13], v42, v34
	v_cmp_gt_f32_e64 s[16:17], v43, v34
	v_cmp_eq_f32_e64 s[18:19], v43, v34
	v_addc_co_u32_e64 v35, s[20:21], v35, v35, s[10:11]
	v_addc_co_u32_e64 v38, s[20:21], v38, v38, s[12:13]
	v_addc_co_u32_e64 v35, s[20:21], v35, v35, s[16:17]
	v_addc_co_u32_e64 v38, s[20:21], v38, v38, s[18:19]
	ds_read_b128 v[40:43], v65 offset:96
	s_waitcnt lgkmcnt(5)
	v_cmp_gt_f32_e64 s[10:11], v44, v34
	v_cmp_eq_f32_e64 s[12:13], v44, v34
	v_cmp_gt_f32_e64 s[16:17], v45, v34
	v_cmp_eq_f32_e64 s[18:19], v45, v34
	v_addc_co_u32_e64 v35, s[20:21], v35, v35, s[10:11]
	v_addc_co_u32_e64 v38, s[20:21], v38, v38, s[12:13]
	v_addc_co_u32_e64 v35, s[20:21], v35, v35, s[16:17]
	v_addc_co_u32_e64 v38, s[20:21], v38, v38, s[18:19]
	v_cmp_gt_f32_e64 s[10:11], v46, v34
	v_cmp_eq_f32_e64 s[12:13], v46, v34
	v_cmp_gt_f32_e64 s[16:17], v47, v34
	v_cmp_eq_f32_e64 s[18:19], v47, v34
	v_addc_co_u32_e64 v35, s[20:21], v35, v35, s[10:11]
	v_addc_co_u32_e64 v38, s[20:21], v38, v38, s[12:13]
	v_addc_co_u32_e64 v35, s[20:21], v35, v35, s[16:17]
	v_addc_co_u32_e64 v38, s[20:21], v38, v38, s[18:19]
	ds_read_b128 v[44:47], v65 offset:112
	s_waitcnt lgkmcnt(5)
	v_cmp_gt_f32_e64 s[10:11], v48, v34
	v_cmp_eq_f32_e64 s[12:13], v48, v34
	v_cmp_gt_f32_e64 s[16:17], v49, v34
	v_cmp_eq_f32_e64 s[18:19], v49, v34
	v_addc_co_u32_e64 v35, s[20:21], v35, v35, s[10:11]
	v_addc_co_u32_e64 v38, s[20:21], v38, v38, s[12:13]
	v_addc_co_u32_e64 v35, s[20:21], v35, v35, s[16:17]
	v_addc_co_u32_e64 v38, s[20:21], v38, v38, s[18:19]
	v_cmp_gt_f32_e64 s[10:11], v50, v34
	v_cmp_eq_f32_e64 s[12:13], v50, v34
	v_cmp_gt_f32_e64 s[16:17], v51, v34
	v_cmp_eq_f32_e64 s[18:19], v51, v34
	v_addc_co_u32_e64 v35, s[20:21], v35, v35, s[10:11]
	v_addc_co_u32_e64 v38, s[20:21], v38, v38, s[12:13]
	v_addc_co_u32_e64 v35, s[20:21], v35, v35, s[16:17]
	v_addc_co_u32_e64 v38, s[20:21], v38, v38, s[18:19]
	ds_read_b32 v64, v226
	ds_read_b128 v[48:51], v65 offset:2048
	s_waitcnt lgkmcnt(6)
	v_cmp_gt_f32_e64 s[10:11], v52, v34
	v_cmp_eq_f32_e64 s[12:13], v52, v34
	v_cmp_gt_f32_e64 s[16:17], v53, v34
	v_cmp_eq_f32_e64 s[18:19], v53, v34
	v_addc_co_u32_e64 v35, s[20:21], v35, v35, s[10:11]
	v_addc_co_u32_e64 v38, s[20:21], v38, v38, s[12:13]
	v_addc_co_u32_e64 v35, s[20:21], v35, v35, s[16:17]
	v_addc_co_u32_e64 v38, s[20:21], v38, v38, s[18:19]
	v_cmp_gt_f32_e64 s[10:11], v54, v34
	v_cmp_eq_f32_e64 s[12:13], v54, v34
	v_cmp_gt_f32_e64 s[16:17], v55, v34
	v_cmp_eq_f32_e64 s[18:19], v55, v34
	v_addc_co_u32_e64 v35, s[20:21], v35, v35, s[10:11]
	v_addc_co_u32_e64 v38, s[20:21], v38, v38, s[12:13]
	v_addc_co_u32_e64 v35, s[20:21], v35, v35, s[16:17]
	v_addc_co_u32_e64 v38, s[20:21], v38, v38, s[18:19]
	ds_read_b128 v[52:55], v65 offset:2064
	s_waitcnt lgkmcnt(6)
	v_cmp_gt_f32_e64 s[10:11], v56, v34
	v_cmp_eq_f32_e64 s[12:13], v56, v34
	v_cmp_gt_f32_e64 s[16:17], v57, v34
	v_cmp_eq_f32_e64 s[18:19], v57, v34
	v_addc_co_u32_e64 v35, s[20:21], v35, v35, s[10:11]
	v_addc_co_u32_e64 v38, s[20:21], v38, v38, s[12:13]
	v_addc_co_u32_e64 v35, s[20:21], v35, v35, s[16:17]
	v_addc_co_u32_e64 v38, s[20:21], v38, v38, s[18:19]
	v_cmp_gt_f32_e64 s[10:11], v58, v34
	v_cmp_eq_f32_e64 s[12:13], v58, v34
	v_cmp_gt_f32_e64 s[16:17], v59, v34
	v_cmp_eq_f32_e64 s[18:19], v59, v34
	v_addc_co_u32_e64 v35, s[20:21], v35, v35, s[10:11]
	v_addc_co_u32_e64 v38, s[20:21], v38, v38, s[12:13]
	v_addc_co_u32_e64 v35, s[20:21], v35, v35, s[16:17]
	v_addc_co_u32_e64 v38, s[20:21], v38, v38, s[18:19]
	ds_read_b128 v[56:59], v65 offset:2080
	s_waitcnt lgkmcnt(6)
	v_cmp_gt_f32_e64 s[10:11], v60, v34
	v_cmp_eq_f32_e64 s[12:13], v60, v34
	v_cmp_gt_f32_e64 s[16:17], v61, v34
	v_cmp_eq_f32_e64 s[18:19], v61, v34
	v_addc_co_u32_e64 v35, s[20:21], v35, v35, s[10:11]
	v_addc_co_u32_e64 v38, s[20:21], v38, v38, s[12:13]
	v_addc_co_u32_e64 v35, s[20:21], v35, v35, s[16:17]
	v_addc_co_u32_e64 v38, s[20:21], v38, v38, s[18:19]
	v_cmp_gt_f32_e64 s[10:11], v62, v34
	v_cmp_eq_f32_e64 s[12:13], v62, v34
	v_cmp_gt_f32_e64 s[16:17], v63, v34
	v_cmp_eq_f32_e64 s[18:19], v63, v34
	v_addc_co_u32_e64 v35, s[20:21], v35, v35, s[10:11]
	v_addc_co_u32_e64 v38, s[20:21], v38, v38, s[12:13]
	v_addc_co_u32_e64 v35, s[20:21], v35, v35, s[16:17]
	v_addc_co_u32_e64 v38, s[20:21], v38, v38, s[18:19]
	ds_read_b128 v[60:63], v65 offset:2096
	s_waitcnt lgkmcnt(6)
	v_cmp_gt_f32_e64 s[10:11], v40, v34
	v_cmp_eq_f32_e64 s[12:13], v40, v34
	v_cmp_gt_f32_e64 s[16:17], v41, v34
	v_cmp_eq_f32_e64 s[18:19], v41, v34
	v_addc_co_u32_e64 v35, s[20:21], v35, v35, s[10:11]
	v_addc_co_u32_e64 v38, s[20:21], v38, v38, s[12:13]
	v_addc_co_u32_e64 v35, s[20:21], v35, v35, s[16:17]
	v_addc_co_u32_e64 v38, s[20:21], v38, v38, s[18:19]
	v_cmp_gt_f32_e64 s[10:11], v42, v34
	v_cmp_eq_f32_e64 s[12:13], v42, v34
	v_cmp_gt_f32_e64 s[16:17], v43, v34
	v_cmp_eq_f32_e64 s[18:19], v43, v34
	v_addc_co_u32_e64 v35, s[20:21], v35, v35, s[10:11]
	v_addc_co_u32_e64 v38, s[20:21], v38, v38, s[12:13]
	v_addc_co_u32_e64 v35, s[20:21], v35, v35, s[16:17]
	v_addc_co_u32_e64 v38, s[20:21], v38, v38, s[18:19]
	ds_read_b128 v[40:43], v65 offset:2112
	s_waitcnt lgkmcnt(6)
; DI void attn_unit(LAS unsigned char* lds, const Args& a, int bg, int qt) {
;     ...
;         for (int it = 0; it < 4; ++it) { const int q = (tid >> 5) + 16 * it;
;             const float v = VAL[q * 32 + j]; int cnt = 0;
; #pragma unroll 8
;             for (int jj = 0; jj < 32; ++jj) { const float ov = VAL[q * 32 + jj]; cnt += ((ov > v) || (ov == v && jj < j)) ? 1 : 0; }
;             const unsigned long long bal = __ballot(cnt < 16);
;             const unsigned mk = ((lane < 32) ? (unsigned)bal : (unsigned)(bal >> 32)) & causal_bits;
;             if ((lane & 31) == 0) MSK[q] = mk; }
	v_cmp_gt_f32_e64 s[10:11], v44, v34
	v_cmp_eq_f32_e64 s[12:13], v44, v34
	v_cmp_gt_f32_e64 s[16:17], v45, v34
	v_cmp_eq_f32_e64 s[18:19], v45, v34
	v_addc_co_u32_e64 v35, s[20:21], v35, v35, s[10:11]
	v_addc_co_u32_e64 v38, s[20:21], v38, v38, s[12:13]
	v_addc_co_u32_e64 v35, s[20:21], v35, v35, s[16:17]
	v_addc_co_u32_e64 v38, s[20:21], v38, v38, s[18:19]
	v_cmp_gt_f32_e64 s[10:11], v46, v34
	v_cmp_eq_f32_e64 s[12:13], v46, v34
	v_cmp_gt_f32_e64 s[16:17], v47, v34
	v_cmp_eq_f32_e64 s[18:19], v47, v34
	v_addc_co_u32_e64 v35, s[20:21], v35, v35, s[10:11]
	v_addc_co_u32_e64 v38, s[20:21], v38, v38, s[12:13]
	v_addc_co_u32_e64 v35, s[20:21], v35, v35, s[16:17]
	v_addc_co_u32_e64 v38, s[20:21], v38, v38, s[18:19]
	ds_read_b128 v[44:47], v65 offset:2128
	v_lshrrev_b32_e64 v39, v98, -1
	v_not_b32_e32 v39, v39
	v_and_b32_e32 v38, v38, v39
	v_bcnt_u32_b32 v35, v35, 0
	v_bcnt_u32_b32 v35, v38, v35
	v_cmp_gt_u32_e32 vcc, 16, v35
	s_and_saveexec_b64 s[10:11], s[6:7]
	s_nop 0
	v_lshrrev_b64 v[38:39], v134, vcc
	v_and_b32_e32 v38, s28, v38
	ds_write_b32 v225, v38
	s_or_b64 exec, exec, s[10:11]
	v_mov_b32_e32 v35, 0
	v_mov_b32_e32 v38, 0
	s_waitcnt lgkmcnt(6)
	v_cmp_gt_f32_e64 s[10:11], v48, v64
	v_cmp_eq_f32_e64 s[12:13], v48, v64
	v_cmp_gt_f32_e64 s[16:17], v49, v64
	v_cmp_eq_f32_e64 s[18:19], v49, v64
	v_addc_co_u32_e64 v35, s[20:21], v35, v35, s[10:11]
	v_addc_co_u32_e64 v38, s[20:21], v38, v38, s[12:13]
	v_addc_co_u32_e64 v35, s[20:21], v35, v35, s[16:17]
	v_addc_co_u32_e64 v38, s[20:21], v38, v38, s[18:19]
	v_cmp_gt_f32_e64 s[10:11], v50, v64
	v_cmp_eq_f32_e64 s[12:13], v50, v64
	v_cmp_gt_f32_e64 s[16:17], v51, v64
	v_cmp_eq_f32_e64 s[18:19], v51, v64
	v_addc_co_u32_e64 v35, s[20:21], v35, v35, s[10:11]
	v_addc_co_u32_e64 v38, s[20:21], v38, v38, s[12:13]
	v_addc_co_u32_e64 v35, s[20:21], v35, v35, s[16:17]
	v_addc_co_u32_e64 v38, s[20:21], v38, v38, s[18:19]
	ds_read_b128 v[48:51], v65 offset:2144
	s_waitcnt lgkmcnt(6)
	v_cmp_gt_f32_e64 s[10:11], v52, v64
	v_cmp_eq_f32_e64 s[12:13], v52, v64
	v_cmp_gt_f32_e64 s[16:17], v53, v64
	v_cmp_eq_f32_e64 s[18:19], v53, v64
	v_addc_co_u32_e64 v35, s[20:21], v35, v35, s[10:11]
	v_addc_co_u32_e64 v38, s[20:21], v38, v38, s[12:13]
	v_addc_co_u32_e64 v35, s[20:21], v35, v35, s[16:17]
	v_addc_co_u32_e64 v38, s[20:21], v38, v38, s[18:19]
	v_cmp_gt_f32_e64 s[10:11], v54, v64
	v_cmp_eq_f32_e64 s[12:13], v54, v64
	v_cmp_gt_f32_e64 s[16:17], v55, v64
	v_cmp_eq_f32_e64 s[18:19], v55, v64
	v_addc_co_u32_e64 v35, s[20:21], v35, v35, s[10:11]
	v_addc_co_u32_e64 v38, s[20:21], v38, v38, s[12:13]
	v_addc_co_u32_e64 v35, s[20:21], v35, v35, s[16:17]
	v_addc_co_u32_e64 v38, s[20:21], v38, v38, s[18:19]
	ds_read_b128 v[52:55], v65 offset:2160
	s_waitcnt lgkmcnt(6)
	v_cmp_gt_f32_e64 s[10:11], v56, v64
	v_cmp_eq_f32_e64 s[12:13], v56, v64
	v_cmp_gt_f32_e64 s[16:17], v57, v64
	v_cmp_eq_f32_e64 s[18:19], v57, v64
	v_addc_co_u32_e64 v35, s[20:21], v35, v35, s[10:11]
	v_addc_co_u32_e64 v38, s[20:21], v38, v38, s[12:13]
	v_addc_co_u32_e64 v35, s[20:21], v35, v35, s[16:17]
	v_addc_co_u32_e64 v38, s[20:21], v38, v38, s[18:19]
	v_cmp_gt_f32_e64 s[10:11], v58, v64
	v_cmp_eq_f32_e64 s[12:13], v58, v64
	v_cmp_gt_f32_e64 s[16:17], v59, v64
	v_cmp_eq_f32_e64 s[18:19], v59, v64
	v_addc_co_u32_e64 v35, s[20:21], v35, v35, s[10:11]
	v_addc_co_u32_e64 v38, s[20:21], v38, v38, s[12:13]
	v_addc_co_u32_e64 v35, s[20:21], v35, v35, s[16:17]
	v_addc_co_u32_e64 v38, s[20:21], v38, v38, s[18:19]
	ds_read_b32 v34, v228
	ds_read_b128 v[56:59], v65 offset:4096
	s_waitcnt lgkmcnt(7)
	v_cmp_gt_f32_e64 s[10:11], v60, v64
	v_cmp_eq_f32_e64 s[12:13], v60, v64
	v_cmp_gt_f32_e64 s[16:17], v61, v64
	v_cmp_eq_f32_e64 s[18:19], v61, v64
	v_addc_co_u32_e64 v35, s[20:21], v35, v35, s[10:11]
	v_addc_co_u32_e64 v38, s[20:21], v38, v38, s[12:13]
	v_addc_co_u32_e64 v35, s[20:21], v35, v35, s[16:17]
	v_addc_co_u32_e64 v38, s[20:21], v38, v38, s[18:19]
	v_cmp_gt_f32_e64 s[10:11], v62, v64
	v_cmp_eq_f32_e64 s[12:13], v62, v64
	v_cmp_gt_f32_e64 s[16:17], v63, v64
	v_cmp_eq_f32_e64 s[18:19], v63, v64
	v_addc_co_u32_e64 v35, s[20:21], v35, v35, s[10:11]
	v_addc_co_u32_e64 v38, s[20:21], v38, v38, s[12:13]
	v_addc_co_u32_e64 v35, s[20:21], v35, v35, s[16:17]
	v_addc_co_u32_e64 v38, s[20:21], v38, v38, s[18:19]
	ds_read_b128 v[60:63], v65 offset:4112
	s_waitcnt lgkmcnt(7)
	v_cmp_gt_f32_e64 s[10:11], v40, v64
	v_cmp_eq_f32_e64 s[12:13], v40, v64
	v_cmp_gt_f32_e64 s[16:17], v41, v64
	v_cmp_eq_f32_e64 s[18:19], v41, v64
	v_addc_co_u32_e64 v35, s[20:21], v35, v35, s[10:11]
	v_addc_co_u32_e64 v38, s[20:21], v38, v38, s[12:13]
	v_addc_co_u32_e64 v35, s[20:21], v35, v35, s[16:17]
	v_addc_co_u32_e64 v38, s[20:21], v38, v38, s[18:19]
	v_cmp_gt_f32_e64 s[10:11], v42, v64
	v_cmp_eq_f32_e64 s[12:13], v42, v64
	v_cmp_gt_f32_e64 s[16:17], v43, v64
	v_cmp_eq_f32_e64 s[18:19], v43, v64
	v_addc_co_u32_e64 v35, s[20:21], v35, v35, s[10:11]
	v_addc_co_u32_e64 v38, s[20:21], v38, v38, s[12:13]
	v_addc_co_u32_e64 v35, s[20:21], v35, v35, s[16:17]
	v_addc_co_u32_e64 v38, s[20:21], v38, v38, s[18:19]
	ds_read_b128 v[40:43], v65 offset:4128
	s_waitcnt lgkmcnt(7)
	v_cmp_gt_f32_e64 s[10:11], v44, v64
	v_cmp_eq_f32_e64 s[12:13], v44, v64
	v_cmp_gt_f32_e64 s[16:17], v45, v64
	v_cmp_eq_f32_e64 s[18:19], v45, v64
	v_addc_co_u32_e64 v35, s[20:21], v35, v35, s[10:11]
	v_addc_co_u32_e64 v38, s[20:21], v38, v38, s[12:13]
	v_addc_co_u32_e64 v35, s[20:21], v35, v35, s[16:17]
	v_addc_co_u32_e64 v38, s[20:21], v38, v38, s[18:19]
	v_cmp_gt_f32_e64 s[10:11], v46, v64
	v_cmp_eq_f32_e64 s[12:13], v46, v64
	v_cmp_gt_f32_e64 s[16:17], v47, v64
	v_cmp_eq_f32_e64 s[18:19], v47, v64
	v_addc_co_u32_e64 v35, s[20:21], v35, v35, s[10:11]
	v_addc_co_u32_e64 v38, s[20:21], v38, v38, s[12:13]
	v_addc_co_u32_e64 v35, s[20:21], v35, v35, s[16:17]
	v_addc_co_u32_e64 v38, s[20:21], v38, v38, s[18:19]
	ds_read_b128 v[44:47], v65 offset:4144
	s_waitcnt lgkmcnt(6)
; DI void attn_unit(LAS unsigned char* lds, const Args& a, int bg, int qt) {
;     ...
;         for (int it = 0; it < 4; ++it) { const int q = (tid >> 5) + 16 * it;
;             const float v = VAL[q * 32 + j]; int cnt = 0;
; #pragma unroll 8
;             for (int jj = 0; jj < 32; ++jj) { const float ov = VAL[q * 32 + jj]; cnt += ((ov > v) || (ov == v && jj < j)) ? 1 : 0; }
;             const unsigned long long bal = __ballot(cnt < 16);
;             const unsigned mk = ((lane < 32) ? (unsigned)bal : (unsigned)(bal >> 32)) & causal_bits;
;             if ((lane & 31) == 0) MSK[q] = mk; }
	v_cmp_gt_f32_e64 s[10:11], v48, v64
	v_cmp_eq_f32_e64 s[12:13], v48, v64
	v_cmp_gt_f32_e64 s[16:17], v49, v64
	v_cmp_eq_f32_e64 s[18:19], v49, v64
	v_addc_co_u32_e64 v35, s[20:21], v35, v35, s[10:11]
	v_addc_co_u32_e64 v38, s[20:21], v38, v38, s[12:13]
	v_addc_co_u32_e64 v35, s[20:21], v35, v35, s[16:17]
	v_addc_co_u32_e64 v38, s[20:21], v38, v38, s[18:19]
	v_cmp_gt_f32_e64 s[10:11], v50, v64
	v_cmp_eq_f32_e64 s[12:13], v50, v64
	v_cmp_gt_f32_e64 s[16:17], v51, v64
	v_cmp_eq_f32_e64 s[18:19], v51, v64
	v_addc_co_u32_e64 v35, s[20:21], v35, v35, s[10:11]
	v_addc_co_u32_e64 v38, s[20:21], v38, v38, s[12:13]
	v_addc_co_u32_e64 v35, s[20:21], v35, v35, s[16:17]
	v_addc_co_u32_e64 v38, s[20:21], v38, v38, s[18:19]
	ds_read_b128 v[48:51], v65 offset:4160
	s_waitcnt lgkmcnt(6)
	v_cmp_gt_f32_e64 s[10:11], v52, v64
	v_cmp_eq_f32_e64 s[12:13], v52, v64
	v_cmp_gt_f32_e64 s[16:17], v53, v64
	v_cmp_eq_f32_e64 s[18:19], v53, v64
	v_addc_co_u32_e64 v35, s[20:21], v35, v35, s[10:11]
	v_addc_co_u32_e64 v38, s[20:21], v38, v38, s[12:13]
	v_addc_co_u32_e64 v35, s[20:21], v35, v35, s[16:17]
	v_addc_co_u32_e64 v38, s[20:21], v38, v38, s[18:19]
	v_cmp_gt_f32_e64 s[10:11], v54, v64
	v_cmp_eq_f32_e64 s[12:13], v54, v64
	v_cmp_gt_f32_e64 s[16:17], v55, v64
	v_cmp_eq_f32_e64 s[18:19], v55, v64
	v_addc_co_u32_e64 v35, s[20:21], v35, v35, s[10:11]
	v_addc_co_u32_e64 v38, s[20:21], v38, v38, s[12:13]
	v_addc_co_u32_e64 v35, s[20:21], v35, v35, s[16:17]
	v_addc_co_u32_e64 v38, s[20:21], v38, v38, s[18:19]
	ds_read_b128 v[52:55], v65 offset:4176
	v_lshrrev_b32_e64 v39, v98, -1
	v_not_b32_e32 v39, v39
	v_and_b32_e32 v38, v38, v39
	v_bcnt_u32_b32 v35, v35, 0
	v_bcnt_u32_b32 v35, v38, v35
	v_cmp_gt_u32_e32 vcc, 16, v35
	s_and_saveexec_b64 s[10:11], s[6:7]
	s_nop 0
	v_lshrrev_b64 v[38:39], v134, vcc
	v_and_b32_e32 v38, s28, v38
	ds_write_b32 v227, v38
	s_or_b64 exec, exec, s[10:11]
	v_mov_b32_e32 v35, 0
	v_mov_b32_e32 v38, 0
	s_waitcnt lgkmcnt(6)
	v_cmp_gt_f32_e64 s[10:11], v56, v34
	v_cmp_eq_f32_e64 s[12:13], v56, v34
	v_cmp_gt_f32_e64 s[16:17], v57, v34
	v_cmp_eq_f32_e64 s[18:19], v57, v34
	v_addc_co_u32_e64 v35, s[20:21], v35, v35, s[10:11]
	v_addc_co_u32_e64 v38, s[20:21], v38, v38, s[12:13]
	v_addc_co_u32_e64 v35, s[20:21], v35, v35, s[16:17]
	v_addc_co_u32_e64 v38, s[20:21], v38, v38, s[18:19]
	v_cmp_gt_f32_e64 s[10:11], v58, v34
	v_cmp_eq_f32_e64 s[12:13], v58, v34
	v_cmp_gt_f32_e64 s[16:17], v59, v34
	v_cmp_eq_f32_e64 s[18:19], v59, v34
	v_addc_co_u32_e64 v35, s[20:21], v35, v35, s[10:11]
	v_addc_co_u32_e64 v38, s[20:21], v38, v38, s[12:13]
	v_addc_co_u32_e64 v35, s[20:21], v35, v35, s[16:17]
	v_addc_co_u32_e64 v38, s[20:21], v38, v38, s[18:19]
	ds_read_b128 v[56:59], v65 offset:4192
	s_waitcnt lgkmcnt(6)
	v_cmp_gt_f32_e64 s[10:11], v60, v34
	v_cmp_eq_f32_e64 s[12:13], v60, v34
	v_cmp_gt_f32_e64 s[16:17], v61, v34
	v_cmp_eq_f32_e64 s[18:19], v61, v34
	v_addc_co_u32_e64 v35, s[20:21], v35, v35, s[10:11]
	v_addc_co_u32_e64 v38, s[20:21], v38, v38, s[12:13]
	v_addc_co_u32_e64 v35, s[20:21], v35, v35, s[16:17]
	v_addc_co_u32_e64 v38, s[20:21], v38, v38, s[18:19]
	v_cmp_gt_f32_e64 s[10:11], v62, v34
	v_cmp_eq_f32_e64 s[12:13], v62, v34
	v_cmp_gt_f32_e64 s[16:17], v63, v34
	v_cmp_eq_f32_e64 s[18:19], v63, v34
	v_addc_co_u32_e64 v35, s[20:21], v35, v35, s[10:11]
	v_addc_co_u32_e64 v38, s[20:21], v38, v38, s[12:13]
	v_addc_co_u32_e64 v35, s[20:21], v35, v35, s[16:17]
	v_addc_co_u32_e64 v38, s[20:21], v38, v38, s[18:19]
	ds_read_b128 v[60:63], v65 offset:4208
	s_waitcnt lgkmcnt(6)
	v_cmp_gt_f32_e64 s[10:11], v40, v34
	v_cmp_eq_f32_e64 s[12:13], v40, v34
	v_cmp_gt_f32_e64 s[16:17], v41, v34
	v_cmp_eq_f32_e64 s[18:19], v41, v34
	v_addc_co_u32_e64 v35, s[20:21], v35, v35, s[10:11]
	v_addc_co_u32_e64 v38, s[20:21], v38, v38, s[12:13]
	v_addc_co_u32_e64 v35, s[20:21], v35, v35, s[16:17]
	v_addc_co_u32_e64 v38, s[20:21], v38, v38, s[18:19]
	v_cmp_gt_f32_e64 s[10:11], v42, v34
	v_cmp_eq_f32_e64 s[12:13], v42, v34
	v_cmp_gt_f32_e64 s[16:17], v43, v34
	v_cmp_eq_f32_e64 s[18:19], v43, v34
	v_addc_co_u32_e64 v35, s[20:21], v35, v35, s[10:11]
	v_addc_co_u32_e64 v38, s[20:21], v38, v38, s[12:13]
	v_addc_co_u32_e64 v35, s[20:21], v35, v35, s[16:17]
	v_addc_co_u32_e64 v38, s[20:21], v38, v38, s[18:19]
	ds_read_b32 v64, v230
	ds_read_b128 v[40:43], v65 offset:6144
	s_waitcnt lgkmcnt(7)
	v_cmp_gt_f32_e64 s[10:11], v44, v34
	v_cmp_eq_f32_e64 s[12:13], v44, v34
	v_cmp_gt_f32_e64 s[16:17], v45, v34
	v_cmp_eq_f32_e64 s[18:19], v45, v34
	v_addc_co_u32_e64 v35, s[20:21], v35, v35, s[10:11]
	v_addc_co_u32_e64 v38, s[20:21], v38, v38, s[12:13]
	v_addc_co_u32_e64 v35, s[20:21], v35, v35, s[16:17]
	v_addc_co_u32_e64 v38, s[20:21], v38, v38, s[18:19]
	v_cmp_gt_f32_e64 s[10:11], v46, v34
	v_cmp_eq_f32_e64 s[12:13], v46, v34
	v_cmp_gt_f32_e64 s[16:17], v47, v34
	v_cmp_eq_f32_e64 s[18:19], v47, v34
	v_addc_co_u32_e64 v35, s[20:21], v35, v35, s[10:11]
	v_addc_co_u32_e64 v38, s[20:21], v38, v38, s[12:13]
	v_addc_co_u32_e64 v35, s[20:21], v35, v35, s[16:17]
	v_addc_co_u32_e64 v38, s[20:21], v38, v38, s[18:19]
	ds_read_b128 v[44:47], v65 offset:6160
	s_waitcnt lgkmcnt(7)
	v_cmp_gt_f32_e64 s[10:11], v48, v34
	v_cmp_eq_f32_e64 s[12:13], v48, v34
	v_cmp_gt_f32_e64 s[16:17], v49, v34
	v_cmp_eq_f32_e64 s[18:19], v49, v34
	v_addc_co_u32_e64 v35, s[20:21], v35, v35, s[10:11]
	v_addc_co_u32_e64 v38, s[20:21], v38, v38, s[12:13]
	v_addc_co_u32_e64 v35, s[20:21], v35, v35, s[16:17]
	v_addc_co_u32_e64 v38, s[20:21], v38, v38, s[18:19]
	v_cmp_gt_f32_e64 s[10:11], v50, v34
	v_cmp_eq_f32_e64 s[12:13], v50, v34
	v_cmp_gt_f32_e64 s[16:17], v51, v34
	v_cmp_eq_f32_e64 s[18:19], v51, v34
	v_addc_co_u32_e64 v35, s[20:21], v35, v35, s[10:11]
	v_addc_co_u32_e64 v38, s[20:21], v38, v38, s[12:13]
	v_addc_co_u32_e64 v35, s[20:21], v35, v35, s[16:17]
	v_addc_co_u32_e64 v38, s[20:21], v38, v38, s[18:19]
	ds_read_b128 v[48:51], v65 offset:6176
	s_waitcnt lgkmcnt(7)
; DI void attn_unit(LAS unsigned char* lds, const Args& a, int bg, int qt) {
;     ...
;         for (int it = 0; it < 4; ++it) { const int q = (tid >> 5) + 16 * it;
;             const float v = VAL[q * 32 + j]; int cnt = 0;
; #pragma unroll 8
;             for (int jj = 0; jj < 32; ++jj) { const float ov = VAL[q * 32 + jj]; cnt += ((ov > v) || (ov == v && jj < j)) ? 1 : 0; }
;             const unsigned long long bal = __ballot(cnt < 16);
;             const unsigned mk = ((lane < 32) ? (unsigned)bal : (unsigned)(bal >> 32)) & causal_bits;
;             if ((lane & 31) == 0) MSK[q] = mk; }
	v_cmp_gt_f32_e64 s[10:11], v52, v34
	v_cmp_eq_f32_e64 s[12:13], v52, v34
	v_cmp_gt_f32_e64 s[16:17], v53, v34
	v_cmp_eq_f32_e64 s[18:19], v53, v34
	v_addc_co_u32_e64 v35, s[20:21], v35, v35, s[10:11]
	v_addc_co_u32_e64 v38, s[20:21], v38, v38, s[12:13]
	v_addc_co_u32_e64 v35, s[20:21], v35, v35, s[16:17]
	v_addc_co_u32_e64 v38, s[20:21], v38, v38, s[18:19]
	v_cmp_gt_f32_e64 s[10:11], v54, v34
	v_cmp_eq_f32_e64 s[12:13], v54, v34
	v_cmp_gt_f32_e64 s[16:17], v55, v34
	v_cmp_eq_f32_e64 s[18:19], v55, v34
	v_addc_co_u32_e64 v35, s[20:21], v35, v35, s[10:11]
	v_addc_co_u32_e64 v38, s[20:21], v38, v38, s[12:13]
	v_addc_co_u32_e64 v35, s[20:21], v35, v35, s[16:17]
	v_addc_co_u32_e64 v38, s[20:21], v38, v38, s[18:19]
	ds_read_b128 v[52:55], v65 offset:6192
	s_waitcnt lgkmcnt(6)
	v_cmp_gt_f32_e64 s[10:11], v56, v34
	v_cmp_eq_f32_e64 s[12:13], v56, v34
	v_cmp_gt_f32_e64 s[16:17], v57, v34
	v_cmp_eq_f32_e64 s[18:19], v57, v34
	v_addc_co_u32_e64 v35, s[20:21], v35, v35, s[10:11]
	v_addc_co_u32_e64 v38, s[20:21], v38, v38, s[12:13]
	v_addc_co_u32_e64 v35, s[20:21], v35, v35, s[16:17]
	v_addc_co_u32_e64 v38, s[20:21], v38, v38, s[18:19]
	v_cmp_gt_f32_e64 s[10:11], v58, v34
	v_cmp_eq_f32_e64 s[12:13], v58, v34
	v_cmp_gt_f32_e64 s[16:17], v59, v34
	v_cmp_eq_f32_e64 s[18:19], v59, v34
	v_addc_co_u32_e64 v35, s[20:21], v35, v35, s[10:11]
	v_addc_co_u32_e64 v38, s[20:21], v38, v38, s[12:13]
	v_addc_co_u32_e64 v35, s[20:21], v35, v35, s[16:17]
	v_addc_co_u32_e64 v38, s[20:21], v38, v38, s[18:19]
	ds_read_b128 v[56:59], v65 offset:6208
	s_waitcnt lgkmcnt(6)
	v_cmp_gt_f32_e64 s[10:11], v60, v34
	v_cmp_eq_f32_e64 s[12:13], v60, v34
	v_cmp_gt_f32_e64 s[16:17], v61, v34
	v_cmp_eq_f32_e64 s[18:19], v61, v34
	v_addc_co_u32_e64 v35, s[20:21], v35, v35, s[10:11]
	v_addc_co_u32_e64 v38, s[20:21], v38, v38, s[12:13]
	v_addc_co_u32_e64 v35, s[20:21], v35, v35, s[16:17]
	v_addc_co_u32_e64 v38, s[20:21], v38, v38, s[18:19]
	v_cmp_gt_f32_e64 s[10:11], v62, v34
	v_cmp_eq_f32_e64 s[12:13], v62, v34
	v_cmp_gt_f32_e64 s[16:17], v63, v34
	v_cmp_eq_f32_e64 s[18:19], v63, v34
	v_addc_co_u32_e64 v35, s[20:21], v35, v35, s[10:11]
	v_addc_co_u32_e64 v38, s[20:21], v38, v38, s[12:13]
	v_addc_co_u32_e64 v35, s[20:21], v35, v35, s[16:17]
	v_addc_co_u32_e64 v38, s[20:21], v38, v38, s[18:19]
	ds_read_b128 v[60:63], v65 offset:6224
	v_lshrrev_b32_e64 v39, v98, -1
	v_not_b32_e32 v39, v39
	v_and_b32_e32 v38, v38, v39
	v_bcnt_u32_b32 v35, v35, 0
	v_bcnt_u32_b32 v35, v38, v35
	v_cmp_gt_u32_e32 vcc, 16, v35
	s_and_saveexec_b64 s[10:11], s[6:7]
	s_nop 0
	v_lshrrev_b64 v[38:39], v134, vcc
	v_and_b32_e32 v38, s28, v38
	ds_write_b32 v229, v38
	s_or_b64 exec, exec, s[10:11]
	v_mov_b32_e32 v35, 0
	v_mov_b32_e32 v38, 0
	s_waitcnt lgkmcnt(6)
	v_cmp_gt_f32_e64 s[10:11], v40, v64
	v_cmp_eq_f32_e64 s[12:13], v40, v64
	v_cmp_gt_f32_e64 s[16:17], v41, v64
	v_cmp_eq_f32_e64 s[18:19], v41, v64
	v_addc_co_u32_e64 v35, s[20:21], v35, v35, s[10:11]
	v_addc_co_u32_e64 v38, s[20:21], v38, v38, s[12:13]
	v_addc_co_u32_e64 v35, s[20:21], v35, v35, s[16:17]
	v_addc_co_u32_e64 v38, s[20:21], v38, v38, s[18:19]
	v_cmp_gt_f32_e64 s[10:11], v42, v64
	v_cmp_eq_f32_e64 s[12:13], v42, v64
	v_cmp_gt_f32_e64 s[16:17], v43, v64
	v_cmp_eq_f32_e64 s[18:19], v43, v64
	v_addc_co_u32_e64 v35, s[20:21], v35, v35, s[10:11]
	v_addc_co_u32_e64 v38, s[20:21], v38, v38, s[12:13]
	v_addc_co_u32_e64 v35, s[20:21], v35, v35, s[16:17]
	v_addc_co_u32_e64 v38, s[20:21], v38, v38, s[18:19]
	ds_read_b128 v[40:43], v65 offset:6240
	s_waitcnt lgkmcnt(6)
	v_cmp_gt_f32_e64 s[10:11], v44, v64
	v_cmp_eq_f32_e64 s[12:13], v44, v64
	v_cmp_gt_f32_e64 s[16:17], v45, v64
	v_cmp_eq_f32_e64 s[18:19], v45, v64
	v_addc_co_u32_e64 v35, s[20:21], v35, v35, s[10:11]
	v_addc_co_u32_e64 v38, s[20:21], v38, v38, s[12:13]
	v_addc_co_u32_e64 v35, s[20:21], v35, v35, s[16:17]
	v_addc_co_u32_e64 v38, s[20:21], v38, v38, s[18:19]
	v_cmp_gt_f32_e64 s[10:11], v46, v64
	v_cmp_eq_f32_e64 s[12:13], v46, v64
	v_cmp_gt_f32_e64 s[16:17], v47, v64
	v_cmp_eq_f32_e64 s[18:19], v47, v64
	v_addc_co_u32_e64 v35, s[20:21], v35, v35, s[10:11]
	v_addc_co_u32_e64 v38, s[20:21], v38, v38, s[12:13]
	v_addc_co_u32_e64 v35, s[20:21], v35, v35, s[16:17]
	v_addc_co_u32_e64 v38, s[20:21], v38, v38, s[18:19]
	ds_read_b128 v[44:47], v65 offset:6256
	s_waitcnt lgkmcnt(6)
	v_cmp_gt_f32_e64 s[10:11], v48, v64
	v_cmp_eq_f32_e64 s[12:13], v48, v64
	v_cmp_gt_f32_e64 s[16:17], v49, v64
	v_cmp_eq_f32_e64 s[18:19], v49, v64
	v_addc_co_u32_e64 v35, s[20:21], v35, v35, s[10:11]
	v_addc_co_u32_e64 v38, s[20:21], v38, v38, s[12:13]
	v_addc_co_u32_e64 v35, s[20:21], v35, v35, s[16:17]
	v_addc_co_u32_e64 v38, s[20:21], v38, v38, s[18:19]
	v_cmp_gt_f32_e64 s[10:11], v50, v64
	v_cmp_eq_f32_e64 s[12:13], v50, v64
	v_cmp_gt_f32_e64 s[16:17], v51, v64
	v_cmp_eq_f32_e64 s[18:19], v51, v64
	v_addc_co_u32_e64 v35, s[20:21], v35, v35, s[10:11]
	v_addc_co_u32_e64 v38, s[20:21], v38, v38, s[12:13]
	v_addc_co_u32_e64 v35, s[20:21], v35, v35, s[16:17]
	v_addc_co_u32_e64 v38, s[20:21], v38, v38, s[18:19]
	s_waitcnt lgkmcnt(5)
; DI void attn_unit(LAS unsigned char* lds, const Args& a, int bg, int qt) {
;     ...
;         for (int it = 0; it < 4; ++it) { const int q = (tid >> 5) + 16 * it;
;             const float v = VAL[q * 32 + j]; int cnt = 0;
; #pragma unroll 8
;             for (int jj = 0; jj < 32; ++jj) { const float ov = VAL[q * 32 + jj]; cnt += ((ov > v) || (ov == v && jj < j)) ? 1 : 0; }
;             const unsigned long long bal = __ballot(cnt < 16);
;             const unsigned mk = ((lane < 32) ? (unsigned)bal : (unsigned)(bal >> 32)) & causal_bits;
;             if ((lane & 31) == 0) MSK[q] = mk; }
;         __syncthreads();
;         if (w == 0) {
;             int ln = lane; asm volatile("" : "+v"(ln));
;             unsigned U = MSK[ln];
; #pragma unroll
;             for (int of = 1; of < 64; of <<= 1) U |= (unsigned)__shfl_xor((int)U, of);
	v_cmp_gt_f32_e64 s[10:11], v52, v64
	v_cmp_eq_f32_e64 s[12:13], v52, v64
	v_cmp_gt_f32_e64 s[16:17], v53, v64
	v_cmp_eq_f32_e64 s[18:19], v53, v64
	v_addc_co_u32_e64 v35, s[20:21], v35, v35, s[10:11]
	v_addc_co_u32_e64 v38, s[20:21], v38, v38, s[12:13]
	v_addc_co_u32_e64 v35, s[20:21], v35, v35, s[16:17]
	v_addc_co_u32_e64 v38, s[20:21], v38, v38, s[18:19]
	v_cmp_gt_f32_e64 s[10:11], v54, v64
	v_cmp_eq_f32_e64 s[12:13], v54, v64
	v_cmp_gt_f32_e64 s[16:17], v55, v64
	v_cmp_eq_f32_e64 s[18:19], v55, v64
	v_addc_co_u32_e64 v35, s[20:21], v35, v35, s[10:11]
	v_addc_co_u32_e64 v38, s[20:21], v38, v38, s[12:13]
	v_addc_co_u32_e64 v35, s[20:21], v35, v35, s[16:17]
	v_addc_co_u32_e64 v38, s[20:21], v38, v38, s[18:19]
	s_waitcnt lgkmcnt(4)
	v_cmp_gt_f32_e64 s[10:11], v56, v64
	v_cmp_eq_f32_e64 s[12:13], v56, v64
	v_cmp_gt_f32_e64 s[16:17], v57, v64
	v_cmp_eq_f32_e64 s[18:19], v57, v64
	v_addc_co_u32_e64 v35, s[20:21], v35, v35, s[10:11]
	v_addc_co_u32_e64 v38, s[20:21], v38, v38, s[12:13]
	v_addc_co_u32_e64 v35, s[20:21], v35, v35, s[16:17]
	v_addc_co_u32_e64 v38, s[20:21], v38, v38, s[18:19]
	v_cmp_gt_f32_e64 s[10:11], v58, v64
	v_cmp_eq_f32_e64 s[12:13], v58, v64
	v_cmp_gt_f32_e64 s[16:17], v59, v64
	v_cmp_eq_f32_e64 s[18:19], v59, v64
	v_addc_co_u32_e64 v35, s[20:21], v35, v35, s[10:11]
	v_addc_co_u32_e64 v38, s[20:21], v38, v38, s[12:13]
	v_addc_co_u32_e64 v35, s[20:21], v35, v35, s[16:17]
	v_addc_co_u32_e64 v38, s[20:21], v38, v38, s[18:19]
	s_waitcnt lgkmcnt(3)
	v_cmp_gt_f32_e64 s[10:11], v60, v64
	v_cmp_eq_f32_e64 s[12:13], v60, v64
	v_cmp_gt_f32_e64 s[16:17], v61, v64
	v_cmp_eq_f32_e64 s[18:19], v61, v64
	v_addc_co_u32_e64 v35, s[20:21], v35, v35, s[10:11]
	v_addc_co_u32_e64 v38, s[20:21], v38, v38, s[12:13]
	v_addc_co_u32_e64 v35, s[20:21], v35, v35, s[16:17]
	v_addc_co_u32_e64 v38, s[20:21], v38, v38, s[18:19]
	v_cmp_gt_f32_e64 s[10:11], v62, v64
	v_cmp_eq_f32_e64 s[12:13], v62, v64
	v_cmp_gt_f32_e64 s[16:17], v63, v64
	v_cmp_eq_f32_e64 s[18:19], v63, v64
	v_addc_co_u32_e64 v35, s[20:21], v35, v35, s[10:11]
	v_addc_co_u32_e64 v38, s[20:21], v38, v38, s[12:13]
	v_addc_co_u32_e64 v35, s[20:21], v35, v35, s[16:17]
	v_addc_co_u32_e64 v38, s[20:21], v38, v38, s[18:19]
	s_waitcnt lgkmcnt(1)
	v_cmp_gt_f32_e64 s[10:11], v40, v64
	v_cmp_eq_f32_e64 s[12:13], v40, v64
	v_cmp_gt_f32_e64 s[16:17], v41, v64
	v_cmp_eq_f32_e64 s[18:19], v41, v64
	v_addc_co_u32_e64 v35, s[20:21], v35, v35, s[10:11]
	v_addc_co_u32_e64 v38, s[20:21], v38, v38, s[12:13]
	v_addc_co_u32_e64 v35, s[20:21], v35, v35, s[16:17]
	v_addc_co_u32_e64 v38, s[20:21], v38, v38, s[18:19]
	v_cmp_gt_f32_e64 s[10:11], v42, v64
	v_cmp_eq_f32_e64 s[12:13], v42, v64
	v_cmp_gt_f32_e64 s[16:17], v43, v64
	v_cmp_eq_f32_e64 s[18:19], v43, v64
	v_addc_co_u32_e64 v35, s[20:21], v35, v35, s[10:11]
	v_addc_co_u32_e64 v38, s[20:21], v38, v38, s[12:13]
	v_addc_co_u32_e64 v35, s[20:21], v35, v35, s[16:17]
	v_addc_co_u32_e64 v38, s[20:21], v38, v38, s[18:19]
	s_waitcnt lgkmcnt(0)
	v_cmp_gt_f32_e64 s[10:11], v44, v64
	v_cmp_eq_f32_e64 s[12:13], v44, v64
	v_cmp_gt_f32_e64 s[16:17], v45, v64
	v_cmp_eq_f32_e64 s[18:19], v45, v64
	v_addc_co_u32_e64 v35, s[20:21], v35, v35, s[10:11]
	v_addc_co_u32_e64 v38, s[20:21], v38, v38, s[12:13]
	v_addc_co_u32_e64 v35, s[20:21], v35, v35, s[16:17]
	v_addc_co_u32_e64 v38, s[20:21], v38, v38, s[18:19]
	v_cmp_gt_f32_e64 s[10:11], v46, v64
	v_cmp_eq_f32_e64 s[12:13], v46, v64
	v_cmp_gt_f32_e64 s[16:17], v47, v64
	v_cmp_eq_f32_e64 s[18:19], v47, v64
	v_addc_co_u32_e64 v35, s[20:21], v35, v35, s[10:11]
	v_addc_co_u32_e64 v38, s[20:21], v38, v38, s[12:13]
	v_addc_co_u32_e64 v35, s[20:21], v35, v35, s[16:17]
	v_addc_co_u32_e64 v38, s[20:21], v38, v38, s[18:19]
	v_lshrrev_b32_e64 v39, v98, -1
	v_not_b32_e32 v39, v39
	v_and_b32_e32 v38, v38, v39
	v_bcnt_u32_b32 v35, v35, 0
	v_bcnt_u32_b32 v35, v38, v35
	v_cmp_gt_u32_e32 vcc, 16, v35
	s_and_saveexec_b64 s[10:11], s[6:7]
	s_nop 0
	v_lshrrev_b64 v[38:39], v134, vcc
	v_and_b32_e32 v38, s28, v38
	ds_write_b32 v231, v38
	s_or_b64 exec, exec, s[10:11]
	s_cmp_gt_u32 s79, 63
	s_waitcnt lgkmcnt(0)
	s_barrier
	s_cbranch_scc1 .LBB0_871
	v_mov_b32_e32 v35, v146
	v_lshl_add_u32 v34, v35, 2, 0
	v_add_u32_e32 v34, 0x1a400, v34
	ds_read_b32 v38, v34
	s_waitcnt lgkmcnt(0)
	s_nop 1
	v_or_b32_dpp v38, v38, v38 quad_perm:[1,0,3,2] row_mask:0xf bank_mask:0xf
	s_nop 1
	v_or_b32_dpp v38, v38, v38 quad_perm:[2,3,0,1] row_mask:0xf bank_mask:0xf
	s_nop 1
	v_or_b32_dpp v38, v38, v38 row_half_mirror row_mask:0xf bank_mask:0xf
	s_nop 1
	v_or_b32_dpp v38, v38, v38 row_mirror row_mask:0xf bank_mask:0xf
	v_mov_b32_e32 v39, v38
	s_nop 1
	v_permlane16_swap_b32_e32 v39, v38
	v_or_b32_e32 v38, v38, v39
	v_mov_b32_e32 v39, v38
	s_nop 1
	v_permlane32_swap_b32_e32 v39, v38
	v_or_b32_e32 v38, v38, v39
	v_cmp_lt_i32_e32 vcc, 31, v35
	v_bcnt_u32_b32 v34, v38, 0
	s_and_saveexec_b64 s[10:11], vcc
	s_xor_b64 s[10:11], exec, s[10:11]
	s_cbranch_execnz .LBB0_878
	s_andn2_saveexec_b64 s[10:11], s[10:11]
	s_cbranch_execnz .LBB0_881
